# attention: all K/V LDS-DMA issued by the first half-workgroup (17 blocks per wave); the second half no longer sleeps - the DMA issue work is the half-workgroup stagger
# speedup vs baseline: 1.0128x; 1.0128x over previous
; #define LAS __attribute__((address_space(3)))
; __device__ __forceinline__ float fexp2(float x) { return __builtin_amdgcn_exp2f(x); }
;     __device__ __forceinline__ PT() { out = (float*)(__attribute__((address_space(1))) float*)ptab_get(23); ws = (unsigned char*)(__attribute__((address_space(1))) unsigned char*)ptab_get(24); }
; #define PREFETCH(t) do { \
;         _Pragma("unroll") for (int i_ = 0; i_ < 4; ++i_) { const int pid_ = tid + 512 * i_, row_ = pid_ >> 4, c16_ = pid_ & 15; const unsigned go_ = (tokb + (unsigned)((t) * 128 + row_)) * 2048u + (unsigned)(hd * 128 + 8 * c16_); \
;             preK[i_] = *(const u32x4*)(Kb + go_); preV[i_] = *(const u32x4*)(Vb + go_); } \
;     } while (0)
; __device__ __forceinline__ void attn_unit(const PT& p, LAS unsigned char* lds, int tid, int lane, int wave, int b, int hd, int qb, float lam) {
;     unsigned char* ws = p.ws;
;     const bf16* Qb = (const bf16*)(ws + WS_Q); const bf16* Kb = (const bf16*)(ws + WS_K); const bf16* Vb = (const bf16*)(ws + WS_VV); const bf16* Gb = (const bf16*)((unsigned char*)p.out + DO_G);
;     bf16* Ob = (bf16*)(ws + WS_O);
;     const int r32 = lane & 31, h = lane >> 5, mp = wave >> 2, wq = wave & 3;
;     const int qw0 = qb * 128 + 32 * wq, q = qw0 + r32; const unsigned tokq = (unsigned)(b * SEQ + q), tokb = (unsigned)(b * SEQ);
;     const float slope2 = fexp2(-0.5f * (float)(hd + 1)) * LOG2E;
;     bf16x8 qf[4];
; #pragma unroll
;     for (int ds = 0; ds < 4; ++ds) qf[ds] = ld_frag16(Qb + (tokq * 2048u + (unsigned)(hd * 128 + mp * 64 + 16 * ds + 8 * h)));
;     float mrun = -INFINITY, lsum = 0.f;
;     f32x16 oT[4];
; #pragma unroll
;     for (int db = 0; db < 4; ++db)
; #pragma unroll
;         for (int i = 0; i < 16; ++i) oT[db][i] = 0.f;
;     const int ntiles = qb + 1;
;     u32x4 preV[4], preK[4];
;     ...
;     PREFETCH(0);
;     const LAS unsigned char* kbase0 = lds + A_KOFF + r32 * AK_PITCH + (mp * 64 + 8 * h) * 2;
;     const LAS unsigned char* vbase0 = lds + A_VOFF + (4 * h + ((lane & 15) >> 2)) * AV_PITCH + ((lane >> 4) & 1) * 32 + (lane & 3) * 8;
; __device__ __forceinline__ void phase_attn(const PT& p, LAS unsigned char* lds, int tid, int lane, int wave) {
;     const float s1 = wave_sum(p.in[16][lane] * p.in[17][lane]), s2 = wave_sum(p.in[18][lane] * p.in[19][lane]);
;     const float lam = __expf(s1) - __expf(s2) + LAMBDA_INIT;
.LBB0_1069:
	s_or_b64 exec, exec, s[0:1]
	s_waitcnt lgkmcnt(0)
	v_mov_b32_e32 v0, 0x23eb8
	s_barrier
	ds_read_b64 v[2:3], v0
	v_mov_b32_e32 v0, 0x23ec0
	ds_read_b64 v[6:7], v0
	v_mov_b32_e32 v0, v196
	v_mov_b32_e32 v1, 0x23e80
	ds_read_b64 v[4:5], v1
	v_mov_b32_e32 v8, 0x23e90
	v_mov_b32_e32 v10, 0x23e98
	ds_read_b64 v[8:9], v8
	ds_read_b64 v[10:11], v10
	s_waitcnt lgkmcnt(2)
	v_readfirstlane_b32 s0, v4
	v_mov_b32_e32 v4, 0x23e88
	v_readfirstlane_b32 s1, v5
	ds_read_b64 v[4:5], v4
	v_and_b32_e32 v198, 63, v0
	v_lshlrev_b32_e32 v1, 2, v198
	s_waitcnt lgkmcnt(2)
	v_readfirstlane_b32 s5, v9
	v_readfirstlane_b32 s4, v8
	s_waitcnt lgkmcnt(0)
	v_readfirstlane_b32 s3, v5
	v_readfirstlane_b32 s2, v4
	v_readfirstlane_b32 s7, v11
	v_readfirstlane_b32 s6, v10
	global_load_dword v4, v1, s[0:1]
	s_nop 1
	global_load_dword v5, v1, s[2:3]
	global_load_dword v8, v1, s[4:5]
	global_load_dword v9, v1, s[6:7]
	v_mbcnt_hi_u32_b32 v1, -1, v182
	v_and_b32_e32 v10, 64, v1
	v_xor_b32_e32 v11, 1, v1
	v_add_u32_e32 v10, 64, v10
	v_cmp_lt_i32_e32 vcc, v11, v10
	v_xor_b32_e32 v12, 2, v1
	v_xor_b32_e32 v13, 4, v1
	v_cndmask_b32_e32 v11, v1, v11, vcc
	v_lshlrev_b32_e32 v11, 2, v11
	v_cmp_lt_i32_e32 vcc, v12, v10
	v_xor_b32_e32 v14, 8, v1
	v_xor_b32_e32 v15, 16, v1
	v_cndmask_b32_e32 v12, v1, v12, vcc
	v_lshlrev_b32_e32 v12, 2, v12
	v_cmp_lt_i32_e32 vcc, v13, v10
	v_xor_b32_e32 v16, 32, v1
	v_readfirstlane_b32 s2, v2
	v_cndmask_b32_e32 v13, v1, v13, vcc
	v_cmp_lt_i32_e32 vcc, v14, v10
	v_readfirstlane_b32 s3, v3
	v_readfirstlane_b32 s0, v7
	v_readfirstlane_b32 s1, v6
	s_cmpk_gt_i32 s90, 0x3ff
	v_readfirstlane_b32 s4, v0
	s_waitcnt vmcnt(2)
	v_mul_f32_e32 v17, v4, v5
	ds_bpermute_b32 v17, v11, v17
	s_waitcnt vmcnt(0)
	v_mul_f32_e32 v18, v8, v9
	ds_bpermute_b32 v11, v11, v18
	s_waitcnt lgkmcnt(1)
	v_fmac_f32_e32 v17, v4, v5
	ds_bpermute_b32 v4, v12, v17
	s_waitcnt lgkmcnt(1)
	v_fmac_f32_e32 v11, v8, v9
	ds_bpermute_b32 v5, v12, v11
	v_lshlrev_b32_e32 v9, 2, v13
	v_cndmask_b32_e32 v8, v1, v14, vcc
	s_waitcnt lgkmcnt(1)
	v_add_f32_e32 v4, v17, v4
	v_lshlrev_b32_e32 v8, 2, v8
	s_waitcnt lgkmcnt(0)
	v_add_f32_e32 v5, v11, v5
	ds_bpermute_b32 v11, v9, v4
	ds_bpermute_b32 v9, v9, v5
	v_cmp_lt_i32_e32 vcc, v15, v10
	s_waitcnt lgkmcnt(1)
	v_add_f32_e32 v4, v4, v11
	s_waitcnt lgkmcnt(0)
	v_add_f32_e32 v5, v5, v9
	ds_bpermute_b32 v9, v8, v4
	ds_bpermute_b32 v8, v8, v5
	v_cndmask_b32_e32 v12, v1, v15, vcc
	v_lshlrev_b32_e32 v179, 2, v12
	v_cmp_lt_i32_e32 vcc, v16, v10
	s_waitcnt lgkmcnt(1)
	v_add_f32_e32 v4, v4, v9
	s_waitcnt lgkmcnt(0)
	v_add_f32_e32 v5, v5, v8
	ds_bpermute_b32 v8, v179, v4
	ds_bpermute_b32 v9, v179, v5
	v_cndmask_b32_e32 v1, v1, v16, vcc
	v_lshlrev_b32_e32 v197, 2, v1
	s_waitcnt lgkmcnt(1)
	v_add_f32_e32 v1, v4, v8
	s_waitcnt lgkmcnt(0)
	v_add_f32_e32 v2, v5, v9
	ds_bpermute_b32 v3, v197, v1
	ds_bpermute_b32 v4, v197, v2
	s_cbranch_scc1 .LBB0_1111
	s_waitcnt lgkmcnt(1)
	v_add_f32_e32 v1, v1, v3
	s_waitcnt lgkmcnt(0)
	v_add_f32_e32 v2, v2, v4
	v_mul_f32_e32 v1, 0x3fb8aa3b, v1
	v_mul_f32_e32 v2, 0x3fb8aa3b, v2
	v_exp_f32_e32 v1, v1
	v_exp_f32_e32 v2, v2
	s_ashr_i32 s36, s4, 6
	s_add_u32 s40, s1, 0x6900000
	s_addc_u32 s41, s0, 0
	v_sub_f32_e32 v1, v1, v2
	s_add_u32 s42, s1, 0x1a900000
	v_lshrrev_b32_e32 v2, 5, v198
	s_addc_u32 s43, s0, 0
	s_ashr_i32 s37, s4, 8
	v_lshlrev_b32_e32 v3, 3, v2
	s_and_b32 s38, s36, 3
	v_lshl_or_b32 v200, s37, 6, v3
	v_lshlrev_b32_e32 v3, 3, v0
	s_add_u32 s44, s1, 0xe900000
	v_and_b32_e32 v201, 0x78, v3
	v_add_u32_e32 v3, 0x200, v0
	s_addc_u32 s45, s0, 0
	v_lshrrev_b32_e32 v203, 4, v3
	v_add_u32_e32 v3, 0x400, v0
	v_add_f32_e32 v199, 0x3eb60549, v1
	v_and_b32_e32 v1, 31, v0
	s_add_u32 s46, s1, 0xa900000
	v_lshrrev_b32_e32 v202, 4, v0
	v_lshrrev_b32_e32 v204, 4, v3
	v_add_u32_e32 v3, 0x600, v0
	v_lshrrev_b32_e32 v4, 2, v0
	v_lshlrev_b32_e32 v0, 4, v0
	s_addc_u32 s47, s0, 0
	s_lshl_b32 s1, s37, 7
	v_lshlrev_b32_e32 v178, 2, v2
	v_and_b32_e32 v0, 0xf0, v0
	v_lshrrev_b32_e32 v205, 4, v3
	s_movk_i32 s0, 0x110
	v_mul_u32_u24_e32 v3, 0x110, v1
	s_add_i32 s1, s1, 0
	v_and_b32_e32 v4, 3, v4
	v_lshl_or_b32 v4, v4, 2, v2
	v_lshlrev_b32_e32 v5, 1, v198
	v_lshlrev_b32_e32 v6, 3, v198
	v_add_u32_e32 v206, 0, v0
	v_lshlrev_b32_e32 v0, 4, v2
	v_and_b32_e32 v5, 32, v5
	v_and_b32_e32 v6, 24, v6
	v_add3_u32 v211, s1, v3, v0
	v_mad_u32_u24 v0, v4, s0, 0
	v_add3_u32 v212, v0, v5, v6
	v_or_b32_e32 v0, 2, v178
	v_cmp_gt_u32_e64 s[6:7], v0, v1
	v_or_b32_e32 v0, 3, v178
	v_cmp_gt_u32_e64 s[8:9], v0, v1
	v_or_b32_e32 v0, 9, v178
	v_cmp_gt_u32_e64 s[12:13], v0, v1
	v_or_b32_e32 v0, 10, v178
	v_cmp_gt_u32_e64 s[14:15], v0, v1
	v_or_b32_e32 v0, 11, v178
	v_cmp_gt_u32_e64 s[16:17], v0, v1
	v_or_b32_e32 v0, 17, v178
	v_cmp_gt_u32_e64 s[20:21], v0, v1
	v_or_b32_e32 v0, 18, v178
	s_cmp_lg_u32 s38, 0
	v_cmp_gt_u32_e64 s[22:23], v0, v1
	v_or_b32_e32 v0, 19, v178
	s_cselect_b64 s[48:49], -1, 0
	s_cmp_eq_u32 s38, 0
	v_cmp_gt_u32_e64 s[24:25], v0, v1
	v_or_b32_e32 v0, 25, v178
	s_cselect_b64 s[50:51], -1, 0
	v_cmp_gt_u32_e64 s[28:29], v0, v1
	v_or_b32_e32 v0, 26, v178
	s_cmp_eq_u32 s38, 1
	v_cmp_gt_u32_e64 s[30:31], v0, v1
	v_or_b32_e32 v0, 27, v178
	s_cselect_b64 s[52:53], -1, 0
	s_cmp_eq_u32 s38, 2
	v_cmp_gt_u32_e64 s[34:35], v0, v1
	v_sub_u32_e64 v0, s38, 1 clamp
	s_cselect_b64 s[54:55], -1, 0
	s_cmp_eq_u32 s38, 3
	v_readfirstlane_b32 s33, v0
	s_cselect_b64 s[56:57], -1, 0
	s_lshl_b32 s39, s38, 14
	v_lshl_or_b32 v0, v205, 11, v201
	v_writelane_b32 v249, s70, 41
	s_add_i32 s86, s39, 0
	v_add_u32_e32 v229, 0x40000, v0
	v_lshl_or_b32 v0, v204, 11, v201
	v_writelane_b32 v249, s71, 42
	s_cmp_eq_u32 s37, 1
	v_add_u32_e32 v230, 0x40000, v0
	v_lshl_or_b32 v0, v203, 11, v201
; #define LAS __attribute__((address_space(3)))
; #define PREFETCH(t) do { \
;         _Pragma("unroll") for (int i_ = 0; i_ < 4; ++i_) { const int pid_ = tid + 512 * i_, row_ = pid_ >> 4, c16_ = pid_ & 15; const unsigned go_ = (tokb + (unsigned)((t) * 128 + row_)) * 2048u + (unsigned)(hd * 128 + 8 * c16_); \
;             preK[i_] = *(const u32x4*)(Kb + go_); preV[i_] = *(const u32x4*)(Vb + go_); } \
;     } while (0)
; __device__ __forceinline__ void attn_unit(const PT& p, LAS unsigned char* lds, int tid, int lane, int wave, int b, int hd, int qb, float lam) {
;     ...
;     PREFETCH(0);
;     const LAS unsigned char* kbase0 = lds + A_KOFF + r32 * AK_PITCH + (mp * 64 + 8 * h) * 2;
;     const LAS unsigned char* vbase0 = lds + A_VOFF + (4 * h + ((lane & 15) >> 2)) * AV_PITCH + ((lane >> 4) & 1) * 32 + (lane & 3) * 8;
	v_or_b32_e32 v213, 8, v178
	v_or_b32_e32 v214, 16, v178
	v_or_b32_e32 v215, 24, v178
	s_cselect_b64 s[58:59], -1, 0
	s_cmp_lt_u32 s36, 4
	v_readlane_b32 s36, v249, 0
	v_add_u32_e32 v231, 0x40000, v0
	v_lshl_or_b32 v0, v202, 11, v201
	s_mov_b32 s62, 2.0
	s_mov_b32 s64, 0x41000000
	s_mov_b32 s66, 0x41200000
	s_mov_b32 s68, 0x41800000
	s_mov_b32 s70, 0x41900000
	s_mov_b32 s72, 0x41c00000
	s_mov_b32 s74, 0x41d00000
	v_mul_lo_u32 v207, v202, s0
	v_mul_lo_u32 v208, v203, s0
	v_mul_lo_u32 v209, v204, s0
	v_mul_lo_u32 v210, v205, s0
	v_cmp_gt_u32_e64 s[0:1], v178, v1
	v_cmp_lt_u32_e64 s[4:5], v178, v1
	v_cmp_gt_u32_e64 s[10:11], v213, v1
	v_cmp_gt_u32_e64 s[18:19], v214, v1
	v_cmp_gt_u32_e64 s[26:27], v215, v1
	s_cselect_b64 s[60:61], -1, 0
	v_mov_b32_e32 v51, 0
	v_or_b32_e32 v216, 32, v178
	v_or_b32_e32 v217, 40, v178
	v_or_b32_e32 v218, 48, v178
	v_or_b32_e32 v219, 56, v178
	v_or_b32_e32 v220, 64, v178
	v_or_b32_e32 v221, 0x48, v178
	v_or_b32_e32 v222, 0x50, v178
	v_or_b32_e32 v223, 0x58, v178
	v_or_b32_e32 v224, 0x60, v178
	v_or_b32_e32 v225, 0x68, v178
	v_or_b32_e32 v226, 0x70, v178
	v_or_b32_e32 v227, 0x78, v178
	v_lshl_or_b32 v228, s38, 5, v1
	s_lshl_b32 s38, s90, 4
	s_lshl_b32 s36, s36, 4
	v_add_u32_e32 v232, 0x40000, v0
	s_mov_b32 s63, 0x40400000
	s_mov_b32 s65, 0x41100000
	s_mov_b32 s67, 0x41300000
	s_mov_b32 s69, 0x41880000
	s_mov_b32 s71, 0x41980000
	s_mov_b32 s73, 0x41c80000
	s_mov_b32 s75, 0x41d80000
	s_mov_b32 s89, 0xff800000
	v_mov_b32_e32 v233, 0x23ea0
	v_mov_b32_e32 v234, 0x3727c5ac
	v_mov_b32_e32 v16, 0xff800000
	v_readlane_b32 s37, v249, 1
	v_writelane_b32 v249, s36, 39
	v_bfe_u32 v0, v196, 6, 2
	v_add_u32_e32 v1, 0, v0
	v_cmp_gt_u32_e32 vcc, 34, v1
	v_subrev_u32_e32 v2, 34, v1
	s_nop 1
	v_cndmask_b32_e32 v1, v2, v1, vcc
	v_lshl_add_u32 v3, v1, 6, v198
	v_mul_u32_u24_e32 v4, 0xf10, v3
	v_lshrrev_b32_e32 v4, 16, v4
	v_mul_u32_u24_e32 v5, 17, v4
	v_sub_u32_e32 v5, v3, v5
	v_min_u32_e32 v5, 15, v5
	v_and_b32_e32 v6, 3, v4
	v_bfe_u32 v7, v4, 2, 2
	v_lshl_or_b32 v6, v6, 2, v7
	v_and_b32_e32 v7, 0xfffffff0, v4
	v_or_b32_e32 v6, v7, v6
	v_cndmask_b32_e32 v4, v6, v4, vcc
	v_lshlrev_b32_e32 v4, 12, v4
	v_lshl_add_u32 v229, v5, 4, v4
	v_add_u32_e32 v1, 4, v0
	v_cmp_gt_u32_e32 vcc, 34, v1
	v_subrev_u32_e32 v2, 34, v1
	s_nop 1
	v_cndmask_b32_e32 v1, v2, v1, vcc
	v_lshl_add_u32 v3, v1, 6, v198
	v_mul_u32_u24_e32 v4, 0xf10, v3
	v_lshrrev_b32_e32 v4, 16, v4
	v_mul_u32_u24_e32 v5, 17, v4
	v_sub_u32_e32 v5, v3, v5
	v_min_u32_e32 v5, 15, v5
	v_and_b32_e32 v6, 3, v4
	v_bfe_u32 v7, v4, 2, 2
	v_lshl_or_b32 v6, v6, 2, v7
	v_and_b32_e32 v7, 0xfffffff0, v4
	v_or_b32_e32 v6, v7, v6
	v_cndmask_b32_e32 v4, v6, v4, vcc
	v_lshlrev_b32_e32 v4, 12, v4
	v_lshl_add_u32 v230, v5, 4, v4
	v_add_u32_e32 v1, 8, v0
	v_cmp_gt_u32_e32 vcc, 34, v1
	v_subrev_u32_e32 v2, 34, v1
	s_nop 1
	v_cndmask_b32_e32 v1, v2, v1, vcc
	v_lshl_add_u32 v3, v1, 6, v198
	v_mul_u32_u24_e32 v4, 0xf10, v3
	v_lshrrev_b32_e32 v4, 16, v4
	v_mul_u32_u24_e32 v5, 17, v4
	v_sub_u32_e32 v5, v3, v5
	v_min_u32_e32 v5, 15, v5
	v_and_b32_e32 v6, 3, v4
	v_bfe_u32 v7, v4, 2, 2
	v_lshl_or_b32 v6, v6, 2, v7
	v_and_b32_e32 v7, 0xfffffff0, v4
	v_or_b32_e32 v6, v7, v6
	v_cndmask_b32_e32 v4, v6, v4, vcc
	v_lshlrev_b32_e32 v4, 12, v4
	v_lshl_add_u32 v231, v5, 4, v4
	v_add_u32_e32 v1, 12, v0
	v_cmp_gt_u32_e32 vcc, 34, v1
	v_subrev_u32_e32 v2, 34, v1
	s_nop 1
	v_cndmask_b32_e32 v1, v2, v1, vcc
	v_lshl_add_u32 v3, v1, 6, v198
	v_mul_u32_u24_e32 v4, 0xf10, v3
	v_lshrrev_b32_e32 v4, 16, v4
	v_mul_u32_u24_e32 v5, 17, v4
	v_sub_u32_e32 v5, v3, v5
	v_min_u32_e32 v5, 15, v5
	v_and_b32_e32 v6, 3, v4
	v_bfe_u32 v7, v4, 2, 2
	v_lshl_or_b32 v6, v6, 2, v7
	v_and_b32_e32 v7, 0xfffffff0, v4
	v_or_b32_e32 v6, v7, v6
	v_cndmask_b32_e32 v4, v6, v4, vcc
	v_lshlrev_b32_e32 v4, 12, v4
	v_lshl_add_u32 v232, v5, 4, v4
	v_add_u32_e32 v1, 16, v0
	v_cmp_gt_u32_e32 vcc, 34, v1
	v_subrev_u32_e32 v2, 34, v1
	s_nop 1
	v_cndmask_b32_e32 v1, v2, v1, vcc
	v_lshl_add_u32 v3, v1, 6, v198
	v_mul_u32_u24_e32 v4, 0xf10, v3
	v_lshrrev_b32_e32 v4, 16, v4
	v_mul_u32_u24_e32 v5, 17, v4
	v_sub_u32_e32 v5, v3, v5
	v_min_u32_e32 v5, 15, v5
	v_and_b32_e32 v6, 3, v4
	v_bfe_u32 v7, v4, 2, 2
	v_lshl_or_b32 v6, v6, 2, v7
	v_and_b32_e32 v7, 0xfffffff0, v4
	v_or_b32_e32 v6, v7, v6
	v_cndmask_b32_e32 v4, v6, v4, vcc
	v_lshlrev_b32_e32 v4, 12, v4
	v_lshl_add_u32 v235, v5, 4, v4
	v_add_u32_e32 v1, 20, v0
	v_cmp_gt_u32_e32 vcc, 34, v1
	v_subrev_u32_e32 v2, 34, v1
	s_nop 1
	v_cndmask_b32_e32 v1, v2, v1, vcc
	v_lshl_add_u32 v3, v1, 6, v198
	v_mul_u32_u24_e32 v4, 0xf10, v3
	v_lshrrev_b32_e32 v4, 16, v4
	v_mul_u32_u24_e32 v5, 17, v4
	v_sub_u32_e32 v5, v3, v5
	v_min_u32_e32 v5, 15, v5
	v_and_b32_e32 v6, 3, v4
	v_bfe_u32 v7, v4, 2, 2
	v_lshl_or_b32 v6, v6, 2, v7
	v_and_b32_e32 v7, 0xfffffff0, v4
	v_or_b32_e32 v6, v7, v6
	v_cndmask_b32_e32 v4, v6, v4, vcc
	v_lshlrev_b32_e32 v4, 12, v4
	v_lshl_add_u32 v236, v5, 4, v4
	v_add_u32_e32 v1, 24, v0
	v_cmp_gt_u32_e32 vcc, 34, v1
	v_subrev_u32_e32 v2, 34, v1
	s_nop 1
	v_cndmask_b32_e32 v1, v2, v1, vcc
	v_lshl_add_u32 v3, v1, 6, v198
	v_mul_u32_u24_e32 v4, 0xf10, v3
	v_lshrrev_b32_e32 v4, 16, v4
	v_mul_u32_u24_e32 v5, 17, v4
	v_sub_u32_e32 v5, v3, v5
	v_min_u32_e32 v5, 15, v5
	v_and_b32_e32 v6, 3, v4
	v_bfe_u32 v7, v4, 2, 2
	v_lshl_or_b32 v6, v6, 2, v7
	v_and_b32_e32 v7, 0xfffffff0, v4
	v_or_b32_e32 v6, v7, v6
	v_cndmask_b32_e32 v4, v6, v4, vcc
	v_lshlrev_b32_e32 v4, 12, v4
	v_lshl_add_u32 v237, v5, 4, v4
; #define LAS __attribute__((address_space(3)))
; #define PREFETCH(t) do { \
;         _Pragma("unroll") for (int i_ = 0; i_ < 4; ++i_) { const int pid_ = tid + 512 * i_, row_ = pid_ >> 4, c16_ = pid_ & 15; const unsigned go_ = (tokb + (unsigned)((t) * 128 + row_)) * 2048u + (unsigned)(hd * 128 + 8 * c16_); \
;             preK[i_] = *(const u32x4*)(Kb + go_); preV[i_] = *(const u32x4*)(Vb + go_); } \
;     } while (0)
; __device__ __forceinline__ void attn_unit(const PT& p, LAS unsigned char* lds, int tid, int lane, int wave, int b, int hd, int qb, float lam) {
;     ...
;     PREFETCH(0);
;     const LAS unsigned char* kbase0 = lds + A_KOFF + r32 * AK_PITCH + (mp * 64 + 8 * h) * 2;
;     const LAS unsigned char* vbase0 = lds + A_VOFF + (4 * h + ((lane & 15) >> 2)) * AV_PITCH + ((lane >> 4) & 1) * 32 + (lane & 3) * 8;
	v_add_u32_e32 v1, 28, v0
	v_cmp_gt_u32_e32 vcc, 34, v1
	v_subrev_u32_e32 v2, 34, v1
	s_nop 1
	v_cndmask_b32_e32 v1, v2, v1, vcc
	v_lshl_add_u32 v3, v1, 6, v198
	v_mul_u32_u24_e32 v4, 0xf10, v3
	v_lshrrev_b32_e32 v4, 16, v4
	v_mul_u32_u24_e32 v5, 17, v4
	v_sub_u32_e32 v5, v3, v5
	v_min_u32_e32 v5, 15, v5
	v_and_b32_e32 v6, 3, v4
	v_bfe_u32 v7, v4, 2, 2
	v_lshl_or_b32 v6, v6, 2, v7
	v_and_b32_e32 v7, 0xfffffff0, v4
	v_or_b32_e32 v6, v7, v6
	v_cndmask_b32_e32 v4, v6, v4, vcc
	v_lshlrev_b32_e32 v4, 12, v4
	v_lshl_add_u32 v238, v5, 4, v4
	v_add_u32_e32 v1, 32, v0
	v_cmp_gt_u32_e32 vcc, 34, v1
	v_subrev_u32_e32 v2, 34, v1
	s_nop 1
	v_cndmask_b32_e32 v1, v2, v1, vcc
	v_lshl_add_u32 v3, v1, 6, v198
	v_mul_u32_u24_e32 v4, 0xf10, v3
	v_lshrrev_b32_e32 v4, 16, v4
	v_mul_u32_u24_e32 v5, 17, v4
	v_sub_u32_e32 v5, v3, v5
	v_min_u32_e32 v5, 15, v5
	v_and_b32_e32 v6, 3, v4
	v_bfe_u32 v7, v4, 2, 2
	v_lshl_or_b32 v6, v6, 2, v7
	v_and_b32_e32 v7, 0xfffffff0, v4
	v_or_b32_e32 v6, v7, v6
	v_cndmask_b32_e32 v4, v6, v4, vcc
	v_lshlrev_b32_e32 v4, 12, v4
	v_lshl_add_u32 v206, v5, 4, v4
	v_add_u32_e32 v1, 36, v0
	v_cmp_gt_u32_e32 vcc, 34, v1
	v_subrev_u32_e32 v2, 34, v1
	s_nop 1
	v_cndmask_b32_e32 v1, v2, v1, vcc
	v_lshl_add_u32 v3, v1, 6, v198
	v_mul_u32_u24_e32 v4, 0xf10, v3
	v_lshrrev_b32_e32 v4, 16, v4
	v_mul_u32_u24_e32 v5, 17, v4
	v_sub_u32_e32 v5, v3, v5
	v_min_u32_e32 v5, 15, v5
	v_and_b32_e32 v6, 3, v4
	v_bfe_u32 v7, v4, 2, 2
	v_lshl_or_b32 v6, v6, 2, v7
	v_and_b32_e32 v7, 0xfffffff0, v4
	v_or_b32_e32 v6, v7, v6
	v_cndmask_b32_e32 v4, v6, v4, vcc
	v_lshlrev_b32_e32 v4, 12, v4
	v_lshl_add_u32 v207, v5, 4, v4
	v_add_u32_e32 v1, 40, v0
	v_cmp_gt_u32_e32 vcc, 34, v1
	v_subrev_u32_e32 v2, 34, v1
	s_nop 1
	v_cndmask_b32_e32 v1, v2, v1, vcc
	v_lshl_add_u32 v3, v1, 6, v198
	v_mul_u32_u24_e32 v4, 0xf10, v3
	v_lshrrev_b32_e32 v4, 16, v4
	v_mul_u32_u24_e32 v5, 17, v4
	v_sub_u32_e32 v5, v3, v5
	v_min_u32_e32 v5, 15, v5
	v_and_b32_e32 v6, 3, v4
	v_bfe_u32 v7, v4, 2, 2
	v_lshl_or_b32 v6, v6, 2, v7
	v_and_b32_e32 v7, 0xfffffff0, v4
	v_or_b32_e32 v6, v7, v6
	v_cndmask_b32_e32 v4, v6, v4, vcc
	v_lshlrev_b32_e32 v4, 12, v4
	v_lshl_add_u32 v208, v5, 4, v4
	v_add_u32_e32 v1, 44, v0
	v_cmp_gt_u32_e32 vcc, 34, v1
	v_subrev_u32_e32 v2, 34, v1
	s_nop 1
	v_cndmask_b32_e32 v1, v2, v1, vcc
	v_lshl_add_u32 v3, v1, 6, v198
	v_mul_u32_u24_e32 v4, 0xf10, v3
	v_lshrrev_b32_e32 v4, 16, v4
	v_mul_u32_u24_e32 v5, 17, v4
	v_sub_u32_e32 v5, v3, v5
	v_min_u32_e32 v5, 15, v5
	v_and_b32_e32 v6, 3, v4
	v_bfe_u32 v7, v4, 2, 2
	v_lshl_or_b32 v6, v6, 2, v7
	v_and_b32_e32 v7, 0xfffffff0, v4
	v_or_b32_e32 v6, v7, v6
	v_cndmask_b32_e32 v4, v6, v4, vcc
	v_lshlrev_b32_e32 v4, 12, v4
	v_lshl_add_u32 v209, v5, 4, v4
	v_add_u32_e32 v1, 48, v0
	v_cmp_gt_u32_e32 vcc, 34, v1
	v_subrev_u32_e32 v2, 34, v1
	s_nop 1
	v_cndmask_b32_e32 v1, v2, v1, vcc
	v_lshl_add_u32 v3, v1, 6, v198
	v_mul_u32_u24_e32 v4, 0xf10, v3
	v_lshrrev_b32_e32 v4, 16, v4
	v_mul_u32_u24_e32 v5, 17, v4
	v_sub_u32_e32 v5, v3, v5
	v_min_u32_e32 v5, 15, v5
	v_and_b32_e32 v6, 3, v4
	v_bfe_u32 v7, v4, 2, 2
	v_lshl_or_b32 v6, v6, 2, v7
	v_and_b32_e32 v7, 0xfffffff0, v4
	v_or_b32_e32 v6, v7, v6
	v_cndmask_b32_e32 v4, v6, v4, vcc
	v_lshlrev_b32_e32 v4, 12, v4
	v_lshl_add_u32 v210, v5, 4, v4
	v_add_u32_e32 v1, 52, v0
	v_cmp_gt_u32_e32 vcc, 34, v1
	v_subrev_u32_e32 v2, 34, v1
	s_nop 1
	v_cndmask_b32_e32 v1, v2, v1, vcc
	v_lshl_add_u32 v3, v1, 6, v198
	v_mul_u32_u24_e32 v4, 0xf10, v3
	v_lshrrev_b32_e32 v4, 16, v4
	v_mul_u32_u24_e32 v5, 17, v4
	v_sub_u32_e32 v5, v3, v5
	v_min_u32_e32 v5, 15, v5
	v_and_b32_e32 v6, 3, v4
	v_bfe_u32 v7, v4, 2, 2
	v_lshl_or_b32 v6, v6, 2, v7
	v_and_b32_e32 v7, 0xfffffff0, v4
	v_or_b32_e32 v6, v7, v6
	v_cndmask_b32_e32 v4, v6, v4, vcc
	v_lshlrev_b32_e32 v4, 12, v4
	v_lshl_add_u32 v184, v5, 4, v4
	v_add_u32_e32 v1, 56, v0
	v_cmp_gt_u32_e32 vcc, 34, v1
	v_subrev_u32_e32 v2, 34, v1
	s_nop 1
	v_cndmask_b32_e32 v1, v2, v1, vcc
	v_lshl_add_u32 v3, v1, 6, v198
	v_mul_u32_u24_e32 v4, 0xf10, v3
	v_lshrrev_b32_e32 v4, 16, v4
	v_mul_u32_u24_e32 v5, 17, v4
	v_sub_u32_e32 v5, v3, v5
	v_min_u32_e32 v5, 15, v5
	v_and_b32_e32 v6, 3, v4
	v_bfe_u32 v7, v4, 2, 2
	v_lshl_or_b32 v6, v6, 2, v7
	v_and_b32_e32 v7, 0xfffffff0, v4
	v_or_b32_e32 v6, v7, v6
	v_cndmask_b32_e32 v4, v6, v4, vcc
	v_lshlrev_b32_e32 v4, 12, v4
	v_lshl_add_u32 v185, v5, 4, v4
	v_add_u32_e32 v1, 60, v0
	v_cmp_gt_u32_e32 vcc, 34, v1
	v_subrev_u32_e32 v2, 34, v1
	s_nop 1
	v_cndmask_b32_e32 v1, v2, v1, vcc
	v_lshl_add_u32 v3, v1, 6, v198
	v_mul_u32_u24_e32 v4, 0xf10, v3
	v_lshrrev_b32_e32 v4, 16, v4
	v_mul_u32_u24_e32 v5, 17, v4
	v_sub_u32_e32 v5, v3, v5
	v_min_u32_e32 v5, 15, v5
	v_and_b32_e32 v6, 3, v4
	v_bfe_u32 v7, v4, 2, 2
	v_lshl_or_b32 v6, v6, 2, v7
	v_and_b32_e32 v7, 0xfffffff0, v4
	v_or_b32_e32 v6, v7, v6
	v_cndmask_b32_e32 v4, v6, v4, vcc
	v_lshlrev_b32_e32 v4, 12, v4
	v_lshl_add_u32 v186, v5, 4, v4
	v_add_u32_e32 v1, 64, v0
	v_cmp_gt_u32_e32 vcc, 34, v1
	v_subrev_u32_e32 v2, 34, v1
	s_nop 1
	v_cndmask_b32_e32 v1, v2, v1, vcc
	v_lshl_add_u32 v3, v1, 6, v198
	v_mul_u32_u24_e32 v4, 0xf10, v3
	v_lshrrev_b32_e32 v4, 16, v4
	v_mul_u32_u24_e32 v5, 17, v4
	v_sub_u32_e32 v5, v3, v5
	v_min_u32_e32 v5, 15, v5
	v_and_b32_e32 v6, 3, v4
	v_bfe_u32 v7, v4, 2, 2
	v_lshl_or_b32 v6, v6, 2, v7
	v_and_b32_e32 v7, 0xfffffff0, v4
	v_or_b32_e32 v6, v7, v6
	v_cndmask_b32_e32 v4, v6, v4, vcc
	v_lshlrev_b32_e32 v4, 12, v4
	v_lshl_add_u32 v187, v5, 4, v4
	s_branch .LBB0_1072

; __device__ __forceinline__ float fexp2(float x) { return __builtin_amdgcn_exp2f(x); }
; __device__ __forceinline__ void attn_unit(const PT& p, LAS unsigned char* lds, int tid, int lane, int wave, int b, int hd, int qb, float lam) {
;     ...
;     const int qw0 = qb * 128 + 32 * wq, q = qw0 + r32; const unsigned tokq = (unsigned)(b * SEQ + q), tokb = (unsigned)(b * SEQ);
;     const float slope2 = fexp2(-0.5f * (float)(hd + 1)) * LOG2E;
;     bf16x8 qf[4];
; #pragma unroll
;     for (int ds = 0; ds < 4; ++ds) qf[ds] = ld_frag16(Qb + (tokq * 2048u + (unsigned)(hd * 128 + mp * 64 + 16 * ds + 8 * h)));
; __device__ __forceinline__ void phase_attn(const PT& p, LAS unsigned char* lds, int tid, int lane, int wave) {
;     ...
;     for (int u = blockIdx.x; u < NBATCH * 16 * 8; u += gridDim.x) {
;         const int j = u & 7, hd = (u >> 3) & 15, b = u >> 7;
; #pragma unroll 1
;         for (int k = 0; k < 2; ++k) attn_unit(p, lds, tid, lane, wave, b, hd, k == 0 ? 15 - j : j, lam);
.LBB0_1072:
	s_and_b32 s98, s90, 0xffffffc0
	s_bfe_u32 s99, s90, 0x30003
	s_or_b32 s98, s98, s99
	s_and_b32 s99, s90, 7
	s_lshl_b32 s99, s99, 3
	s_or_b32 s98, s98, s99
	s_lshr_b32 s99, s90, 8
	s_and_b32 s36, s99, 1
	s_mul_i32 s36, s36, 7
	s_lshr_b32 s99, s99, 1
	s_lshl_b32 s99, s99, 3
	s_or_b32 s99, s99, s36
	s_lshl_b32 s36, s98, 15
	s_bfe_u32 s37, s98, 0x40003
	s_xor_b32 s37, s37, s99
	s_and_b32 s36, s36, 0xffc00000
	s_lshl_b32 s91, s37, 7
	s_or_b32 s36, s91, s36
	s_add_i32 s37, s37, 1
	s_lshl_b32 s36, s98, 4
	v_cvt_f32_ubyte0_e32 v0, s37
	s_and_b32 s94, s36, 0xfffff800
	v_mul_f32_e32 v0, -0.5, v0
	v_exp_f32_e32 v2, v0
	v_or_b32_e32 v3, s91, v201
	v_add_u32_e32 v0, s94, v202
	v_lshl_or_b32 v50, v0, 11, v3
	v_lshlrev_b64 v[0:1], 1, v[50:51]
	v_add_u32_e32 v0, s94, v203
	v_lshl_or_b32 v50, v0, 11, v3
	v_lshlrev_b64 v[0:1], 1, v[50:51]
	v_add_u32_e32 v0, s94, v204
	v_lshl_or_b32 v50, v0, 11, v3
	v_lshlrev_b64 v[0:1], 1, v[50:51]
	v_add_u32_e32 v0, s94, v205
	v_lshl_or_b32 v50, v0, 11, v3
	s_and_b32 s92, s98, 7
	v_lshlrev_b64 v[0:1], 1, v[50:51]
	s_xor_b32 s93, s92, 15
	v_add_u32_e32 v239, s91, v200
	v_mul_f32_e32 v240, 0x3fb8aa3b, v2
	s_mov_b64 s[36:37], -1
	v_writelane_b32 v249, s38, 37
	s_branch .LBB0_1074

; #define LAS __attribute__((address_space(3)))
; #define PREFETCH(t) do { \
;         _Pragma("unroll") for (int i_ = 0; i_ < 4; ++i_) { const int pid_ = tid + 512 * i_, row_ = pid_ >> 4, c16_ = pid_ & 15; const unsigned go_ = (tokb + (unsigned)((t) * 128 + row_)) * 2048u + (unsigned)(hd * 128 + 8 * c16_); \
;             preK[i_] = *(const u32x4*)(Kb + go_); preV[i_] = *(const u32x4*)(Vb + go_); } \
;     } while (0)
; #define STAGE_WRITE(stg) do { \
;         _Pragma("unroll") for (int i_ = 0; i_ < 4; ++i_) { const int pid_ = tid + 512 * i_, row_ = pid_ >> 4, c16_ = pid_ & 15; \
;             *(LAS u32x4*)(lds + (stg) * A_STAGE + A_KOFF + row_ * AK_PITCH + 16 * c16_) = preK[i_]; *(LAS u32x4*)(lds + (stg) * A_STAGE + A_VOFF + row_ * AV_PITCH + 16 * c16_) = preV[i_]; } \
;     } while (0)
; __device__ __forceinline__ void attn_unit(const PT& p, LAS unsigned char* lds, int tid, int lane, int wave, int b, int hd, int qb, float lam) {
;     ...
;     PREFETCH(0);
;     const LAS unsigned char* kbase0 = lds + A_KOFF + r32 * AK_PITCH + (mp * 64 + 8 * h) * 2;
;     const LAS unsigned char* vbase0 = lds + A_VOFF + (4 * h + ((lane & 15) >> 2)) * AV_PITCH + ((lane >> 4) & 1) * 32 + (lane & 3) * 8;
;     ...
;     __syncthreads();
;     STAGE_WRITE(0);
;     asm volatile("" : "+v"(qf[0]), "+v"(qf[1]), "+v"(qf[2]), "+v"(qf[3]));
;     __syncthreads();
.LBB0_1074:
	s_xor_b64 s[76:77], s[36:37], -1
	s_and_b64 s[36:37], s[36:37], exec
	s_cselect_b32 s95, s93, s92
	v_lshl_or_b32 v8, s95, 7, v228
	v_or_b32_e32 v0, s94, v8
	v_lshlrev_b32_e32 v241, 11, v0
	v_add_u32_e32 v50, v239, v241
	v_lshl_add_u64 v[0:1], v[50:51], 1, s[40:41]
	v_or_b32_e32 v2, 16, v50
	v_mov_b32_e32 v3, v51
	v_or_b32_e32 v4, 32, v50
	v_mov_b32_e32 v5, v51
	v_or_b32_e32 v50, 48, v50
	v_lshl_add_u64 v[2:3], v[2:3], 1, s[40:41]
	v_lshl_add_u64 v[4:5], v[4:5], 1, s[40:41]
	v_lshl_add_u64 v[6:7], v[50:51], 1, s[40:41]
	s_lshl_b32 s96, s95, 18
	global_load_dwordx4 v[130:133], v[0:1], off
	global_load_dwordx4 v[142:145], v[6:7], off
	global_load_dwordx4 v[146:149], v[4:5], off
	global_load_dwordx4 v[150:153], v[2:3], off
	s_barrier
	s_and_b64 vcc, exec, s[58:59]
	s_cbranch_vccnz .Ldma_skip1
	s_mov_b32 s98, s96
	s_lshl_b32 s99, s94, 11
	s_add_i32 s99, s99, s91
	s_add_i32 s99, s99, s98
	s_lshl_b32 s99, s99, 1
	s_mov_b32 s87, 0
	v_readfirstlane_b32 s100, v196
	s_lshr_b32 s100, s100, 6
	s_cmp_lt_u32 s100, 2
	s_cselect_b32 s36, s46, s42
	s_cselect_b32 s37, s47, s43
	s_lshl_b32 s100, s100, 10
	s_add_i32 s100, s100, s87
	s_mov_b32 m0, s100
	v_add_u32_e32 v50, s99, v229
	global_load_lds_dwordx4 v50, s[46:47]
	s_add_i32 m0, s100, 0x1000
	v_add_u32_e32 v50, s99, v230
	global_load_lds_dwordx4 v50, s[46:47]
	s_add_i32 m0, s100, 0x2000
	v_add_u32_e32 v50, s99, v231
	global_load_lds_dwordx4 v50, s[46:47]
	s_add_i32 m0, s100, 0x3000
	v_add_u32_e32 v50, s99, v232
	global_load_lds_dwordx4 v50, s[46:47]
	s_add_i32 m0, s100, 0x4000
	v_add_u32_e32 v50, s99, v235
	global_load_lds_dwordx4 v50, s[46:47]
	s_add_i32 m0, s100, 0x5000
	v_add_u32_e32 v50, s99, v236
	global_load_lds_dwordx4 v50, s[46:47]
	s_add_i32 m0, s100, 0x6000
	v_add_u32_e32 v50, s99, v237
	global_load_lds_dwordx4 v50, s[46:47]
	s_add_i32 m0, s100, 0x7000
	v_add_u32_e32 v50, s99, v238
	global_load_lds_dwordx4 v50, s[46:47]
	s_add_i32 m0, s100, 0x8000
	v_add_u32_e32 v50, s99, v206
	global_load_lds_dwordx4 v50, s[36:37]
	s_add_i32 m0, s100, 0x9000
	v_add_u32_e32 v50, s99, v207
	global_load_lds_dwordx4 v50, s[42:43]
	s_add_i32 m0, s100, 0xa000
	v_add_u32_e32 v50, s99, v208
	global_load_lds_dwordx4 v50, s[42:43]
	s_add_i32 m0, s100, 0xb000
	v_add_u32_e32 v50, s99, v209
	global_load_lds_dwordx4 v50, s[42:43]
	s_add_i32 m0, s100, 0xc000
	v_add_u32_e32 v50, s99, v210
	global_load_lds_dwordx4 v50, s[42:43]
	s_add_i32 m0, s100, 0xd000
	v_add_u32_e32 v50, s99, v184
	global_load_lds_dwordx4 v50, s[42:43]
	s_add_i32 m0, s100, 0xe000
	v_add_u32_e32 v50, s99, v185
	global_load_lds_dwordx4 v50, s[42:43]
	s_add_i32 m0, s100, 0xf000
	v_add_u32_e32 v50, s99, v186
	global_load_lds_dwordx4 v50, s[42:43]
	s_add_i32 m0, s100, 0x10000
	v_add_u32_e32 v50, s99, v187
	global_load_lds_dwordx4 v50, s[42:43]
.Ldma_skip1:
	v_mov_b32_e32 v64, v51
	v_mov_b32_e32 v65, v51
	s_lshl_b32 s96, s95, 18
	v_mov_b32_e32 v50, v51
	v_mov_b32_e32 v52, v51
	v_mov_b32_e32 v53, v51
	v_mov_b32_e32 v54, v51
	v_mov_b32_e32 v55, v51
	v_mov_b32_e32 v56, v51
	v_mov_b32_e32 v57, v51
	v_mov_b32_e32 v58, v51
	v_mov_b32_e32 v59, v51
	v_mov_b32_e32 v60, v51
	v_mov_b32_e32 v61, v51
	v_mov_b32_e32 v62, v51
	v_mov_b32_e32 v63, v51
	v_mov_b64_e32 v[80:81], v[64:65]
	v_mov_b64_e32 v[96:97], v[64:65]
	v_mov_b64_e32 v[112:113], v[64:65]
	v_mov_b64_e32 v[128:129], v[64:65]
	v_sub_u32_e32 v242, v178, v8
	v_lshl_add_u32 v242, s95, 7, v242
	s_mov_b32 s97, 0xfffc0000
	s_mov_b32 s38, s96
	v_mov_b32_e32 v248, 0xff800000
	v_mov_b32_e32 v243, 0
	v_mov_b64_e32 v[78:79], v[62:63]
	v_mov_b64_e32 v[76:77], v[60:61]
	v_mov_b64_e32 v[74:75], v[58:59]
	v_mov_b64_e32 v[72:73], v[56:57]
	v_mov_b64_e32 v[70:71], v[54:55]
	v_mov_b64_e32 v[68:69], v[52:53]
	v_mov_b64_e32 v[66:67], v[50:51]
	v_mov_b64_e32 v[94:95], v[62:63]
	v_mov_b64_e32 v[92:93], v[60:61]
	v_mov_b64_e32 v[90:91], v[58:59]
	v_mov_b64_e32 v[88:89], v[56:57]
	v_mov_b64_e32 v[86:87], v[54:55]
	v_mov_b64_e32 v[84:85], v[52:53]
	v_mov_b64_e32 v[82:83], v[50:51]
	v_mov_b64_e32 v[110:111], v[62:63]
	v_mov_b64_e32 v[108:109], v[60:61]
	v_mov_b64_e32 v[106:107], v[58:59]
	v_mov_b64_e32 v[104:105], v[56:57]
	v_mov_b64_e32 v[102:103], v[54:55]
	v_mov_b64_e32 v[100:101], v[52:53]
	v_mov_b64_e32 v[98:99], v[50:51]
	v_mov_b64_e32 v[126:127], v[62:63]
	v_mov_b64_e32 v[124:125], v[60:61]
	v_mov_b64_e32 v[122:123], v[58:59]
	v_mov_b64_e32 v[120:121], v[56:57]
	v_mov_b64_e32 v[118:119], v[54:55]
	v_mov_b64_e32 v[116:117], v[52:53]
	v_mov_b64_e32 v[114:115], v[50:51]
	s_mov_b32 s39, 0
	s_waitcnt vmcnt(0)
	s_waitcnt lgkmcnt(0)
	s_barrier
	s_branch .LBB0_1076

; #define LAS __attribute__((address_space(3)))
; #define PREFETCH(t) do { \
;         _Pragma("unroll") for (int i_ = 0; i_ < 4; ++i_) { const int pid_ = tid + 512 * i_, row_ = pid_ >> 4, c16_ = pid_ & 15; const unsigned go_ = (tokb + (unsigned)((t) * 128 + row_)) * 2048u + (unsigned)(hd * 128 + 8 * c16_); \
;             preK[i_] = *(const u32x4*)(Kb + go_); preV[i_] = *(const u32x4*)(Vb + go_); } \
;     } while (0)
; #define STAGE_WRITE(stg) do { \
;         _Pragma("unroll") for (int i_ = 0; i_ < 4; ++i_) { const int pid_ = tid + 512 * i_, row_ = pid_ >> 4, c16_ = pid_ & 15; \
;             *(LAS u32x4*)(lds + (stg) * A_STAGE + A_KOFF + row_ * AK_PITCH + 16 * c16_) = preK[i_]; *(LAS u32x4*)(lds + (stg) * A_STAGE + A_VOFF + row_ * AV_PITCH + 16 * c16_) = preV[i_]; } \
;     } while (0)
; __device__ __forceinline__ void attn_unit(const PT& p, LAS unsigned char* lds, int tid, int lane, int wave, int b, int hd, int qb, float lam) {
;     ...
;         const int stg = t & 1;
;         if (t + 1 < ntiles) PREFETCH(t + 1);
;         const LAS unsigned char* kbase = kbase0 + stg * A_STAGE; const LAS unsigned char* vbase = vbase0 + stg * A_STAGE;
;         const bool diag = (t == qb);
; #pragma unroll 2
;         for (int sub = 0; sub < 2; ++sub) {
;             const int nact = diag ? min(2, max(0, wq + 1 - 2 * sub)) : 2;
;             if (nact > 0) {
;                 float sl = slope2; asm volatile("" : "+v"(sl));
;                 const float bq = sl * (float)(t * 128 + sub * 64 + 4 * h - q);
;                 const LAS unsigned char* kb0 = kbase + sub * 64 * AK_PITCH; const LAS unsigned char* vb0 = vbase + sub * 64 * AV_PITCH;
;     ...
;         if (t + 1 < ntiles) STAGE_WRITE(stg ^ 1);
.LBB0_1076:
	s_cmp_lt_u32 s39, s95
	s_cselect_b64 s[78:79], -1, 0
	s_cmp_ge_u32 s39, s95
	s_cbranch_scc1 .LBB0_1078
	s_and_b64 vcc, exec, s[58:59]
	s_cbranch_vccnz .Ldma_skip2
	s_sub_i32 s98, s38, 0x40000
	s_lshl_b32 s99, s94, 11
	s_add_i32 s99, s99, s91
	s_add_i32 s99, s99, s98
	s_lshl_b32 s99, s99, 1
	s_and_b32 s87, s39, 1
	s_xor_b32 s87, s87, 1
	s_mul_i32 s87, s87, 0x11000
	v_readfirstlane_b32 s100, v196
	s_lshr_b32 s100, s100, 6
	s_cmp_lt_u32 s100, 2
	s_cselect_b32 s36, s46, s42
	s_cselect_b32 s37, s47, s43
	s_lshl_b32 s100, s100, 10
	s_add_i32 s100, s100, s87
	s_mov_b32 m0, s100
	v_add_u32_e32 v50, s99, v229
	global_load_lds_dwordx4 v50, s[46:47]
	s_add_i32 m0, s100, 0x1000
	v_add_u32_e32 v50, s99, v230
	global_load_lds_dwordx4 v50, s[46:47]
	s_add_i32 m0, s100, 0x2000
	v_add_u32_e32 v50, s99, v231
	global_load_lds_dwordx4 v50, s[46:47]
	s_add_i32 m0, s100, 0x3000
	v_add_u32_e32 v50, s99, v232
	global_load_lds_dwordx4 v50, s[46:47]
	s_add_i32 m0, s100, 0x4000
	v_add_u32_e32 v50, s99, v235
	global_load_lds_dwordx4 v50, s[46:47]
	s_add_i32 m0, s100, 0x5000
	v_add_u32_e32 v50, s99, v236
	global_load_lds_dwordx4 v50, s[46:47]
	s_add_i32 m0, s100, 0x6000
	v_add_u32_e32 v50, s99, v237
	global_load_lds_dwordx4 v50, s[46:47]
	s_add_i32 m0, s100, 0x7000
	v_add_u32_e32 v50, s99, v238
	global_load_lds_dwordx4 v50, s[46:47]
	s_add_i32 m0, s100, 0x8000
	v_add_u32_e32 v50, s99, v206
	global_load_lds_dwordx4 v50, s[36:37]
	s_add_i32 m0, s100, 0x9000
	v_add_u32_e32 v50, s99, v207
	global_load_lds_dwordx4 v50, s[42:43]
	s_add_i32 m0, s100, 0xa000
	v_add_u32_e32 v50, s99, v208
	global_load_lds_dwordx4 v50, s[42:43]
	s_add_i32 m0, s100, 0xb000
	v_add_u32_e32 v50, s99, v209
	global_load_lds_dwordx4 v50, s[42:43]
	s_add_i32 m0, s100, 0xc000
	v_add_u32_e32 v50, s99, v210
	global_load_lds_dwordx4 v50, s[42:43]
	s_add_i32 m0, s100, 0xd000
	v_add_u32_e32 v50, s99, v184
	global_load_lds_dwordx4 v50, s[42:43]
	s_add_i32 m0, s100, 0xe000
	v_add_u32_e32 v50, s99, v185
	global_load_lds_dwordx4 v50, s[42:43]
	s_add_i32 m0, s100, 0xf000
	v_add_u32_e32 v50, s99, v186
	global_load_lds_dwordx4 v50, s[42:43]
	s_add_i32 m0, s100, 0x10000
	v_add_u32_e32 v50, s99, v187
	global_load_lds_dwordx4 v50, s[42:43]
.Ldma_skip2:
.LBB0_1078:
	s_and_b32 s87, s39, 1
	s_mul_i32 s88, s87, 0x11000
	v_add_u32_e32 v56, s88, v211
	s_add_i32 s36, s88, 0x8800
	v_add_u32_e32 v254, s36, v212
	s_cmp_lg_u32 s96, s38
	s_cselect_b64 s[82:83], -1, 0
	s_cmp_eq_u32 s96, s38
	s_cselect_b64 s[80:81], -1, 0
	s_or_b64 s[84:85], s[48:49], s[82:83]
	s_and_b64 vcc, exec, s[58:59]
	s_cbranch_vccz .Lat_nostagger
	s_nop 0
